# batched loads instead of load->wait chains: fin light items (4 rows per wait), adaLN GEMV rows (16 per wait, counted waits), attention epilogue gain fragments (8 per wait)
# speedup vs baseline: 1.0329x; 1.0141x over previous
.LBB0_466:
	v_lshl_add_u64 v[58:59], v[50:51], 0, s[28:29]
	v_lshl_add_u64 v[56:57], v[52:53], 0, s[28:29]
	v_add_co_u32_e32 v60, vcc, 0x1000000, v58
	s_nop 1
	v_addc_co_u32_e32 v61, vcc, 0, v59, vcc
	v_add_co_u32_e32 v54, vcc, 0xfffff800, v54
	s_nop 1
	v_addc_co_u32_e32 v55, vcc, -1, v55, vcc
	s_mov_b32 s28, 0
.Lfinl_loop:
	global_load_dword v214, v[58:59], off
	global_load_dword v215, v[60:61], off
	global_load_ushort v216, v[54:55], off
	global_load_dword v217, v[58:59], off offset:1024
	global_load_dword v218, v[60:61], off offset:1024
	global_load_ushort v219, v[54:55], off offset:512
	global_load_dword v220, v[58:59], off offset:2048
	global_load_dword v221, v[60:61], off offset:2048
	global_load_ushort v194, v[54:55], off offset:1024
	global_load_dword v195, v[58:59], off offset:3072
	global_load_dword v243, v[60:61], off offset:3072
	global_load_ushort v248, v[54:55], off offset:1536
	s_waitcnt vmcnt(0)
	v_add_f32_e32 v67, v214, v215
	s_nop 1
	v_add_f32_dpp v68, v67, v67 quad_perm:[1,0,3,2] row_mask:0xf bank_mask:0xf bound_ctrl:1
	s_nop 1
	v_add_f32_dpp v68, v68, v68 quad_perm:[2,3,0,1] row_mask:0xf bank_mask:0xf bound_ctrl:1
	s_nop 1
	v_add_f32_dpp v68, v68, v68 row_half_mirror row_mask:0xf bank_mask:0xf bound_ctrl:1
	s_nop 1
	v_add_f32_dpp v68, v68, v68 row_mirror row_mask:0xf bank_mask:0xf bound_ctrl:1
	v_mov_b32_e32 v69, v68
	s_nop 1
	v_permlane16_swap_b32_e32 v68, v69
	v_add_f32_e32 v68, v68, v69
	v_mov_b32_e32 v69, v68
	s_nop 1
	v_permlane32_swap_b32_e32 v68, v69
	v_add_f32_e32 v68, v68, v69
	v_fmac_f32_e32 v67, 0xbc800000, v68
	v_mul_f32_e32 v68, v67, v67
	s_nop 1
	v_mov_b32_dpp v68, v68 quad_perm:[1,0,3,2] row_mask:0xf bank_mask:0xf bound_ctrl:1
	v_fmac_f32_e32 v68, v67, v67
	s_nop 1
	v_add_f32_dpp v68, v68, v68 quad_perm:[2,3,0,1] row_mask:0xf bank_mask:0xf bound_ctrl:1
	s_nop 1
	v_add_f32_dpp v68, v68, v68 row_half_mirror row_mask:0xf bank_mask:0xf bound_ctrl:1
	s_nop 1
	v_add_f32_dpp v68, v68, v68 row_mirror row_mask:0xf bank_mask:0xf bound_ctrl:1
	v_mov_b32_e32 v69, v68
	s_nop 1
	v_permlane16_swap_b32_e32 v68, v69
	v_add_f32_e32 v68, v68, v69
	v_mov_b32_e32 v69, v68
	s_nop 1
	v_permlane32_swap_b32_e32 v68, v69
	v_add_f32_e32 v68, v68, v69
	v_fmamk_f32 v68, v68, 0x3c800000, v202
	v_cmp_gt_f32_e32 vcc, s4, v68
	v_mul_f32_e32 v69, 0x4b800000, v68
	s_nop 0
	v_cndmask_b32_e32 v68, v68, v69, vcc
	v_rsq_f32_e32 v68, v68
	s_nop 0
	v_mul_f32_e32 v69, 0x45800000, v68
	v_cndmask_b32_e32 v68, v68, v69, vcc
	v_mul_f32_e32 v67, v67, v68
	v_fma_f32 v67, v0, v67, v63
	v_lshlrev_b32_e32 v68, 16, v216
	v_mul_f32_e32 v67, v67, v68
	v_cvt_pk_bf16_f32 v67, v67, s0
	global_store_short v[56:57], v67, off offset:1024
	v_add_f32_e32 v67, v217, v218
	s_nop 1
	v_add_f32_dpp v68, v67, v67 quad_perm:[1,0,3,2] row_mask:0xf bank_mask:0xf bound_ctrl:1
	s_nop 1
	v_add_f32_dpp v68, v68, v68 quad_perm:[2,3,0,1] row_mask:0xf bank_mask:0xf bound_ctrl:1
	s_nop 1
	v_add_f32_dpp v68, v68, v68 row_half_mirror row_mask:0xf bank_mask:0xf bound_ctrl:1
	s_nop 1
	v_add_f32_dpp v68, v68, v68 row_mirror row_mask:0xf bank_mask:0xf bound_ctrl:1
	v_mov_b32_e32 v69, v68
	s_nop 1
	v_permlane16_swap_b32_e32 v68, v69
	v_add_f32_e32 v68, v68, v69
	v_mov_b32_e32 v69, v68
	s_nop 1
	v_permlane32_swap_b32_e32 v68, v69
	v_add_f32_e32 v68, v68, v69
	v_fmac_f32_e32 v67, 0xbc800000, v68
	v_mul_f32_e32 v68, v67, v67
	s_nop 1
	v_mov_b32_dpp v68, v68 quad_perm:[1,0,3,2] row_mask:0xf bank_mask:0xf bound_ctrl:1
	v_fmac_f32_e32 v68, v67, v67
	s_nop 1
	v_add_f32_dpp v68, v68, v68 quad_perm:[2,3,0,1] row_mask:0xf bank_mask:0xf bound_ctrl:1
	s_nop 1
	v_add_f32_dpp v68, v68, v68 row_half_mirror row_mask:0xf bank_mask:0xf bound_ctrl:1
	s_nop 1
	v_add_f32_dpp v68, v68, v68 row_mirror row_mask:0xf bank_mask:0xf bound_ctrl:1
	v_mov_b32_e32 v69, v68
	s_nop 1
	v_permlane16_swap_b32_e32 v68, v69
	v_add_f32_e32 v68, v68, v69
	v_mov_b32_e32 v69, v68
	s_nop 1
	v_permlane32_swap_b32_e32 v68, v69
	v_add_f32_e32 v68, v68, v69
	v_fmamk_f32 v68, v68, 0x3c800000, v202
	v_cmp_gt_f32_e32 vcc, s4, v68
	v_mul_f32_e32 v69, 0x4b800000, v68
	s_nop 0
	v_cndmask_b32_e32 v68, v68, v69, vcc
	v_rsq_f32_e32 v68, v68
	s_nop 0
	v_mul_f32_e32 v69, 0x45800000, v68
	v_cndmask_b32_e32 v68, v68, v69, vcc
	v_mul_f32_e32 v67, v67, v68
	v_fma_f32 v67, v62, v67, v64
	v_lshlrev_b32_e32 v68, 16, v219
	v_mul_f32_e32 v67, v67, v68
	v_cvt_pk_bf16_f32 v67, v67, s0
	global_store_short v[56:57], v67, off offset:1536
	v_add_f32_e32 v67, v220, v221
	s_nop 1
	v_add_f32_dpp v68, v67, v67 quad_perm:[1,0,3,2] row_mask:0xf bank_mask:0xf bound_ctrl:1
	s_nop 1
	v_add_f32_dpp v68, v68, v68 quad_perm:[2,3,0,1] row_mask:0xf bank_mask:0xf bound_ctrl:1
	s_nop 1
	v_add_f32_dpp v68, v68, v68 row_half_mirror row_mask:0xf bank_mask:0xf bound_ctrl:1
	s_nop 1
	v_add_f32_dpp v68, v68, v68 row_mirror row_mask:0xf bank_mask:0xf bound_ctrl:1
	v_mov_b32_e32 v69, v68
	s_nop 1
	v_permlane16_swap_b32_e32 v68, v69
	v_add_f32_e32 v68, v68, v69
	v_mov_b32_e32 v69, v68
	s_nop 1
	v_permlane32_swap_b32_e32 v68, v69
	v_add_f32_e32 v68, v68, v69
	v_fmac_f32_e32 v67, 0xbc800000, v68
	v_mul_f32_e32 v68, v67, v67
	s_nop 1
	v_mov_b32_dpp v68, v68 quad_perm:[1,0,3,2] row_mask:0xf bank_mask:0xf bound_ctrl:1
	v_fmac_f32_e32 v68, v67, v67
	s_nop 1
	v_add_f32_dpp v68, v68, v68 quad_perm:[2,3,0,1] row_mask:0xf bank_mask:0xf bound_ctrl:1
	s_nop 1
	v_add_f32_dpp v68, v68, v68 row_half_mirror row_mask:0xf bank_mask:0xf bound_ctrl:1
	s_nop 1
	v_add_f32_dpp v68, v68, v68 row_mirror row_mask:0xf bank_mask:0xf bound_ctrl:1
	v_mov_b32_e32 v69, v68
	s_nop 1
	v_permlane16_swap_b32_e32 v68, v69
	v_add_f32_e32 v68, v68, v69
	v_mov_b32_e32 v69, v68
	s_nop 1
	v_permlane32_swap_b32_e32 v68, v69
	v_add_f32_e32 v68, v68, v69
	v_fmamk_f32 v68, v68, 0x3c800000, v202
	v_cmp_gt_f32_e32 vcc, s4, v68
	v_mul_f32_e32 v69, 0x4b800000, v68
	s_nop 0
	v_cndmask_b32_e32 v68, v68, v69, vcc
	v_rsq_f32_e32 v68, v68
	s_nop 0
	v_mul_f32_e32 v69, 0x45800000, v68
	v_cndmask_b32_e32 v68, v68, v69, vcc
	v_mul_f32_e32 v67, v67, v68
	v_fma_f32 v67, v0, v67, v63
	v_lshlrev_b32_e32 v68, 16, v194
	v_mul_f32_e32 v67, v67, v68
	v_cvt_pk_bf16_f32 v67, v67, s0
	global_store_short v[56:57], v67, off offset:3072
	v_add_f32_e32 v67, v195, v243
	s_nop 1
	v_add_f32_dpp v68, v67, v67 quad_perm:[1,0,3,2] row_mask:0xf bank_mask:0xf bound_ctrl:1
	s_nop 1
	v_add_f32_dpp v68, v68, v68 quad_perm:[2,3,0,1] row_mask:0xf bank_mask:0xf bound_ctrl:1
	s_nop 1
	v_add_f32_dpp v68, v68, v68 row_half_mirror row_mask:0xf bank_mask:0xf bound_ctrl:1
	s_nop 1
	v_add_f32_dpp v68, v68, v68 row_mirror row_mask:0xf bank_mask:0xf bound_ctrl:1
	v_mov_b32_e32 v69, v68
	s_nop 1
	v_permlane16_swap_b32_e32 v68, v69
	v_add_f32_e32 v68, v68, v69
	v_mov_b32_e32 v69, v68
	s_nop 1
	v_permlane32_swap_b32_e32 v68, v69
	v_add_f32_e32 v68, v68, v69
	v_fmac_f32_e32 v67, 0xbc800000, v68
	v_mul_f32_e32 v68, v67, v67
	s_nop 1
	v_mov_b32_dpp v68, v68 quad_perm:[1,0,3,2] row_mask:0xf bank_mask:0xf bound_ctrl:1
	v_fmac_f32_e32 v68, v67, v67
	s_nop 1
	v_add_f32_dpp v68, v68, v68 quad_perm:[2,3,0,1] row_mask:0xf bank_mask:0xf bound_ctrl:1
	s_nop 1
	v_add_f32_dpp v68, v68, v68 row_half_mirror row_mask:0xf bank_mask:0xf bound_ctrl:1
	s_nop 1
	v_add_f32_dpp v68, v68, v68 row_mirror row_mask:0xf bank_mask:0xf bound_ctrl:1
	v_mov_b32_e32 v69, v68
	s_nop 1
	v_permlane16_swap_b32_e32 v68, v69
	v_add_f32_e32 v68, v68, v69
	v_mov_b32_e32 v69, v68
	s_nop 1
	v_permlane32_swap_b32_e32 v68, v69
	v_add_f32_e32 v68, v68, v69
	v_fmamk_f32 v68, v68, 0x3c800000, v202
	v_cmp_gt_f32_e32 vcc, s4, v68
	v_mul_f32_e32 v69, 0x4b800000, v68
	s_nop 0
	v_cndmask_b32_e32 v68, v68, v69, vcc
	v_rsq_f32_e32 v68, v68
	s_nop 0
	v_mul_f32_e32 v69, 0x45800000, v68
	v_cndmask_b32_e32 v68, v68, v69, vcc
	v_mul_f32_e32 v67, v67, v68
	v_fma_f32 v67, v62, v67, v64
	v_lshlrev_b32_e32 v68, 16, v248
	v_mul_f32_e32 v67, v67, v68
	v_cvt_pk_bf16_f32 v67, v67, s0
	global_store_short v[56:57], v67, off offset:3584
	v_add_co_u32_e32 v58, vcc, 0x1000, v58
	s_nop 1
	v_addc_co_u32_e32 v59, vcc, 0, v59, vcc
	v_add_co_u32_e32 v60, vcc, 0x1000, v60
	s_nop 1
	v_addc_co_u32_e32 v61, vcc, 0, v61, vcc
	v_add_co_u32_e32 v56, vcc, 0x1000, v56
	s_nop 1
	v_addc_co_u32_e32 v57, vcc, 0, v57, vcc
	v_add_co_u32_e32 v54, vcc, 0x800, v54
	s_nop 1
	v_addc_co_u32_e32 v55, vcc, 0, v55, vcc
	s_add_i32 s28, s28, 1
	s_cmp_lg_u32 s28, 4
	s_cbranch_scc1 .Lfinl_loop
	s_movk_i32 s28, 0x4000
	s_mov_b64 s[0:1], 0

.LBB0_519:
	v_readlane_b32 s20, v255, 26
	v_readlane_b32 s21, v255, 27
	v_mul_f32_e32 v0, v80, v80
	v_mul_f32_e32 v16, v81, v81
	v_mul_f32_e32 v17, v82, v82
	v_fmac_f32_e32 v0, v96, v96
	v_fmac_f32_e32 v16, v97, v97
	global_load_dwordx4 v[178:181], v128, s[20:21]
	global_load_dwordx4 v[182:185], v128, s[20:21] offset:32
	global_load_dwordx4 v[186:189], v128, s[20:21] offset:64
	global_load_dwordx4 v[190:193], v128, s[20:21] offset:96
	global_load_dwordx4 v[232:235], v128, s[20:21] offset:128
	global_load_dwordx4 v[236:239], v128, s[20:21] offset:160
	global_load_dwordx4 v[240:243], v128, s[20:21] offset:192
	global_load_dwordx4 v[244:247], v128, s[20:21] offset:224
	v_mul_f32_e32 v18, v83, v83
	v_fmac_f32_e32 v17, v98, v98
	v_add_f32_e32 v0, v0, v16
	v_mul_f32_e32 v19, v84, v84
	v_fmac_f32_e32 v18, v99, v99
	v_add_f32_e32 v0, v17, v0
	v_mul_f32_e32 v20, v85, v85
	v_fmac_f32_e32 v19, v100, v100
	v_add_f32_e32 v0, v18, v0
	v_pk_mul_f32 v[6:7], v[86:87], v[86:87]
	v_fmac_f32_e32 v20, v101, v101
	v_add_f32_e32 v0, v19, v0
	v_pk_fma_f32 v[6:7], v[102:103], v[102:103], v[6:7]
	v_add_f32_e32 v0, v20, v0
	v_pk_mul_f32 v[8:9], v[88:89], v[88:89]
	v_add_f32_e32 v0, v6, v0
	s_waitcnt vmcnt(6)
	v_pk_fma_f32 v[8:9], v[104:105], v[104:105], v[8:9]
	v_add_f32_e32 v0, v7, v0
	v_pk_mul_f32 v[10:11], v[90:91], v[90:91]
	v_add_f32_e32 v0, v8, v0
	v_pk_fma_f32 v[10:11], v[106:107], v[106:107], v[10:11]
	v_add_f32_e32 v0, v9, v0
	v_pk_mul_f32 v[12:13], v[92:93], v[92:93]
	v_add_f32_e32 v0, v10, v0
	s_waitcnt vmcnt(5)
	v_pk_fma_f32 v[12:13], v[108:109], v[108:109], v[12:13]
	v_add_f32_e32 v0, v11, v0
	v_pk_mul_f32 v[14:15], v[94:95], v[94:95]
	v_add_f32_e32 v0, v12, v0
	v_pk_fma_f32 v[14:15], v[110:111], v[110:111], v[14:15]
	v_add_f32_e32 v0, v13, v0
	v_add_f32_e32 v0, v14, v0
	v_add_f32_e32 v8, v15, v0
	v_mov_b32_e32 v9, v8
	s_nop 1
	v_permlane32_swap_b32_e32 v8, v9
	s_lshl_b32 s0, s29, 11
	s_addk_i32 s0, 0x1000
	v_or3_b32 v0, v161, s0, v160
	v_lshlrev_b64 v[6:7], 11, v[0:1]
	s_waitcnt lgkmcnt(0)
	v_add_f32_e32 v0, v8, v9
	v_mov_b32_e32 v8, 0x3727c5ac
	v_fmamk_f32 v0, v0, 0x3c800000, v8
	s_mov_b32 s0, 0x800000
	v_mul_f32_e32 v8, 0x4b800000, v0
	v_cmp_gt_f32_e32 vcc, s0, v0
	v_readlane_b32 s4, v254, 0
	v_readlane_b32 s6, v254, 2
	v_cndmask_b32_e32 v0, v0, v8, vcc
	v_rsq_f32_e32 v0, v0
	v_readlane_b32 s7, v254, 3
	s_lshl_b32 s30, s28, 7
	v_mov_b32_e32 v131, v1
	v_mul_f32_e32 v8, 0x45800000, v0
	v_cndmask_b32_e32 v0, v0, v8, vcc
	v_mul_f32_e32 v0, v159, v0
	v_lshl_add_u64 v[6:7], s[6:7], 0, v[6:7]
	v_pk_mul_f32 v[8:9], v[96:97], v[0:1] op_sel_hi:[1,0]
	v_pk_mul_f32 v[10:11], v[98:99], v[0:1] op_sel_hi:[1,0]
	v_lshl_add_u64 v[6:7], v[6:7], 0, s[30:31]
	v_lshl_add_u64 v[6:7], v[6:7], 0, v[130:131]
	v_readlane_b32 s5, v254, 1
	v_readlane_b32 s8, v254, 4
	v_readlane_b32 s9, v254, 5
	v_readlane_b32 s10, v254, 6
	v_readlane_b32 s11, v254, 7
	v_readlane_b32 s12, v254, 8
	v_readlane_b32 s13, v254, 9
	v_readlane_b32 s14, v254, 10
	v_readlane_b32 s15, v254, 11
	v_readlane_b32 s16, v254, 12
	v_readlane_b32 s17, v254, 13
	v_readlane_b32 s18, v254, 14
	v_readlane_b32 s19, v254, 15
	s_mov_b64 s[0:1], 0
	s_waitcnt vmcnt(0)
	v_mov_b64_e32 v[2:3], v[178:179]
	v_mov_b64_e32 v[4:5], v[180:181]
	v_pk_mul_f32 v[2:3], v[2:3], v[8:9]
	v_pk_mul_f32 v[4:5], v[4:5], v[10:11]
	v_cvt_pk_bf16_f32 v2, v2, v3
	v_cvt_pk_bf16_f32 v3, v4, v5
	global_store_dwordx2 v[6:7], v[2:3], off
	v_mov_b64_e32 v[2:3], v[182:183]
	v_mov_b64_e32 v[4:5], v[184:185]
	v_pk_mul_f32 v[8:9], v[100:101], v[0:1] op_sel_hi:[1,0]
	v_pk_mul_f32 v[10:11], v[102:103], v[0:1] op_sel_hi:[1,0]
	v_pk_mul_f32 v[2:3], v[2:3], v[8:9]
	v_pk_mul_f32 v[4:5], v[4:5], v[10:11]
	v_cvt_pk_bf16_f32 v2, v2, v3
	v_cvt_pk_bf16_f32 v3, v4, v5
	global_store_dwordx2 v[6:7], v[2:3], off offset:16
	v_mov_b64_e32 v[2:3], v[186:187]
	v_mov_b64_e32 v[4:5], v[188:189]
	v_pk_mul_f32 v[8:9], v[104:105], v[0:1] op_sel_hi:[1,0]
	v_pk_mul_f32 v[10:11], v[106:107], v[0:1] op_sel_hi:[1,0]
	v_pk_mul_f32 v[2:3], v[8:9], v[2:3]
	v_pk_mul_f32 v[4:5], v[10:11], v[4:5]
	v_cvt_pk_bf16_f32 v2, v2, v3
	v_cvt_pk_bf16_f32 v3, v4, v5
	global_store_dwordx2 v[6:7], v[2:3], off offset:32
	v_mov_b64_e32 v[2:3], v[190:191]
	v_mov_b64_e32 v[4:5], v[192:193]
	v_pk_mul_f32 v[8:9], v[108:109], v[0:1] op_sel_hi:[1,0]
	v_pk_mul_f32 v[10:11], v[110:111], v[0:1] op_sel_hi:[1,0]
	v_pk_mul_f32 v[2:3], v[8:9], v[2:3]
	v_pk_mul_f32 v[4:5], v[10:11], v[4:5]
	v_cvt_pk_bf16_f32 v2, v2, v3
	v_cvt_pk_bf16_f32 v3, v4, v5
	global_store_dwordx2 v[6:7], v[2:3], off offset:48
	v_mov_b64_e32 v[2:3], v[232:233]
	v_mov_b64_e32 v[4:5], v[234:235]
	v_pk_mul_f32 v[8:9], v[80:81], v[0:1] op_sel_hi:[1,0]
	v_pk_mul_f32 v[10:11], v[82:83], v[0:1] op_sel_hi:[1,0]
	v_pk_mul_f32 v[2:3], v[8:9], v[2:3]
	v_pk_mul_f32 v[4:5], v[10:11], v[4:5]
	v_cvt_pk_bf16_f32 v2, v2, v3
	v_cvt_pk_bf16_f32 v3, v4, v5
	global_store_dwordx2 v[6:7], v[2:3], off offset:64
	v_mov_b64_e32 v[2:3], v[236:237]
	v_mov_b64_e32 v[4:5], v[238:239]
	v_pk_mul_f32 v[8:9], v[84:85], v[0:1] op_sel_hi:[1,0]
	v_pk_mul_f32 v[10:11], v[86:87], v[0:1] op_sel_hi:[1,0]
	v_pk_mul_f32 v[2:3], v[8:9], v[2:3]
	v_pk_mul_f32 v[4:5], v[10:11], v[4:5]
	v_cvt_pk_bf16_f32 v2, v2, v3
	v_cvt_pk_bf16_f32 v3, v4, v5
	global_store_dwordx2 v[6:7], v[2:3], off offset:80
	v_mov_b64_e32 v[2:3], v[240:241]
	v_mov_b64_e32 v[4:5], v[242:243]
	v_pk_mul_f32 v[8:9], v[88:89], v[0:1] op_sel_hi:[1,0]
	v_pk_mul_f32 v[10:11], v[90:91], v[0:1] op_sel_hi:[1,0]
	v_pk_mul_f32 v[2:3], v[8:9], v[2:3]
	v_pk_mul_f32 v[4:5], v[10:11], v[4:5]
	v_cvt_pk_bf16_f32 v2, v2, v3
	v_cvt_pk_bf16_f32 v3, v4, v5
	global_store_dwordx2 v[6:7], v[2:3], off offset:96
	v_mov_b64_e32 v[2:3], v[244:245]
	v_mov_b64_e32 v[4:5], v[246:247]
	v_pk_mul_f32 v[8:9], v[92:93], v[0:1] op_sel_hi:[1,0]
	v_pk_mul_f32 v[10:11], v[94:95], v[0:1] op_sel_hi:[1,0]
	v_pk_mul_f32 v[2:3], v[8:9], v[2:3]
	v_pk_mul_f32 v[4:5], v[10:11], v[4:5]
	v_cvt_pk_bf16_f32 v2, v2, v3
	v_cvt_pk_bf16_f32 v3, v4, v5
	global_store_dwordx2 v[6:7], v[2:3], off offset:112

.LBB0_541:
	v_readlane_b32 s20, v255, 26
	v_readlane_b32 s21, v255, 27
	v_mul_f32_e32 v0, v66, v66
	v_mul_f32_e32 v16, v67, v67
	v_mul_f32_e32 v17, v68, v68
	v_fmac_f32_e32 v0, v82, v82
	v_fmac_f32_e32 v16, v83, v83
	global_load_dwordx4 v[178:181], v122, s[20:21]
	global_load_dwordx4 v[182:185], v122, s[20:21] offset:32
	global_load_dwordx4 v[186:189], v122, s[20:21] offset:64
	global_load_dwordx4 v[190:193], v122, s[20:21] offset:96
	global_load_dwordx4 v[232:235], v122, s[20:21] offset:128
	global_load_dwordx4 v[236:239], v122, s[20:21] offset:160
	global_load_dwordx4 v[240:243], v122, s[20:21] offset:192
	global_load_dwordx4 v[244:247], v122, s[20:21] offset:224
	v_mul_f32_e32 v18, v69, v69
	v_fmac_f32_e32 v17, v84, v84
	v_add_f32_e32 v0, v0, v16
	v_mul_f32_e32 v19, v70, v70
	v_fmac_f32_e32 v18, v85, v85
	v_add_f32_e32 v0, v17, v0
	v_mul_f32_e32 v20, v71, v71
	v_fmac_f32_e32 v19, v86, v86
	v_add_f32_e32 v0, v18, v0
	v_pk_mul_f32 v[6:7], v[72:73], v[72:73]
	v_fmac_f32_e32 v20, v87, v87
	v_add_f32_e32 v0, v19, v0
	v_pk_fma_f32 v[6:7], v[88:89], v[88:89], v[6:7]
	v_add_f32_e32 v0, v20, v0
	v_pk_mul_f32 v[8:9], v[74:75], v[74:75]
	v_add_f32_e32 v0, v6, v0
	v_pk_fma_f32 v[8:9], v[90:91], v[90:91], v[8:9]
	v_add_f32_e32 v0, v7, v0
	v_pk_mul_f32 v[10:11], v[76:77], v[76:77]
	v_add_f32_e32 v0, v8, v0
	v_pk_fma_f32 v[10:11], v[92:93], v[92:93], v[10:11]
	v_add_f32_e32 v0, v9, v0
	v_pk_mul_f32 v[12:13], v[78:79], v[78:79]
	v_add_f32_e32 v0, v10, v0
	v_pk_fma_f32 v[12:13], v[94:95], v[94:95], v[12:13]
	v_add_f32_e32 v0, v11, v0
	v_pk_mul_f32 v[14:15], v[80:81], v[80:81]
	v_add_f32_e32 v0, v12, v0
	v_pk_fma_f32 v[14:15], v[96:97], v[96:97], v[14:15]
	v_add_f32_e32 v0, v13, v0
	v_add_f32_e32 v0, v14, v0
	v_add_f32_e32 v8, v15, v0
	v_mov_b32_e32 v9, v8
	s_nop 1
	v_permlane32_swap_b32_e32 v8, v9
	s_lshl_b32 s0, s44, 8
	v_or3_b32 v0, v148, s0, v147
	v_lshlrev_b64 v[6:7], 11, v[0:1]
	s_mov_b32 s0, 0x800000
	s_waitcnt lgkmcnt(0)
	v_add_f32_e32 v0, v8, v9
	v_mov_b32_e32 v8, 0x3727c5ac
	v_fmamk_f32 v0, v0, 0x3c800000, v8
	v_mul_f32_e32 v8, 0x4b800000, v0
	v_cmp_gt_f32_e32 vcc, s0, v0
	v_readlane_b32 s4, v254, 0
	v_readlane_b32 s6, v254, 2
	v_cndmask_b32_e32 v0, v0, v8, vcc
	v_rsq_f32_e32 v0, v0
	v_readlane_b32 s7, v254, 3
	s_lshl_b32 s30, s43, 7
	v_mov_b32_e32 v125, v1
	v_mul_f32_e32 v8, 0x45800000, v0
	v_cndmask_b32_e32 v0, v0, v8, vcc
	v_mul_f32_e32 v0, v159, v0
	v_lshl_add_u64 v[6:7], s[6:7], 0, v[6:7]
	v_pk_mul_f32 v[8:9], v[82:83], v[0:1] op_sel_hi:[1,0]
	v_pk_mul_f32 v[10:11], v[84:85], v[0:1] op_sel_hi:[1,0]
	v_lshl_add_u64 v[6:7], v[6:7], 0, s[30:31]
	v_lshl_add_u64 v[6:7], v[6:7], 0, v[124:125]
	s_mov_b32 s23, s45
	v_readlane_b32 s5, v254, 1
	v_readlane_b32 s8, v254, 4
	v_readlane_b32 s9, v254, 5
	v_readlane_b32 s10, v254, 6
	v_readlane_b32 s11, v254, 7
	v_readlane_b32 s12, v254, 8
	v_readlane_b32 s13, v254, 9
	v_readlane_b32 s14, v254, 10
	v_readlane_b32 s15, v254, 11
	v_readlane_b32 s16, v254, 12
	v_readlane_b32 s17, v254, 13
	v_readlane_b32 s18, v254, 14
	v_readlane_b32 s19, v254, 15
	s_waitcnt vmcnt(0)
	v_mov_b64_e32 v[2:3], v[178:179]
	v_mov_b64_e32 v[4:5], v[180:181]
	v_pk_mul_f32 v[2:3], v[2:3], v[8:9]
	v_pk_mul_f32 v[4:5], v[4:5], v[10:11]
	v_cvt_pk_bf16_f32 v2, v2, v3
	v_cvt_pk_bf16_f32 v3, v4, v5
	global_store_dwordx2 v[6:7], v[2:3], off
	v_mov_b64_e32 v[2:3], v[182:183]
	v_mov_b64_e32 v[4:5], v[184:185]
	v_pk_mul_f32 v[8:9], v[86:87], v[0:1] op_sel_hi:[1,0]
	v_pk_mul_f32 v[10:11], v[88:89], v[0:1] op_sel_hi:[1,0]
	v_pk_mul_f32 v[2:3], v[2:3], v[8:9]
	v_pk_mul_f32 v[4:5], v[4:5], v[10:11]
	v_cvt_pk_bf16_f32 v2, v2, v3
	v_cvt_pk_bf16_f32 v3, v4, v5
	global_store_dwordx2 v[6:7], v[2:3], off offset:16
	v_mov_b64_e32 v[2:3], v[186:187]
	v_mov_b64_e32 v[4:5], v[188:189]
	v_pk_mul_f32 v[8:9], v[90:91], v[0:1] op_sel_hi:[1,0]
	v_pk_mul_f32 v[10:11], v[92:93], v[0:1] op_sel_hi:[1,0]
	v_pk_mul_f32 v[2:3], v[8:9], v[2:3]
	v_pk_mul_f32 v[4:5], v[10:11], v[4:5]
	v_cvt_pk_bf16_f32 v2, v2, v3
	v_cvt_pk_bf16_f32 v3, v4, v5
	global_store_dwordx2 v[6:7], v[2:3], off offset:32
	v_mov_b64_e32 v[2:3], v[190:191]
	v_mov_b64_e32 v[4:5], v[192:193]
	v_pk_mul_f32 v[8:9], v[94:95], v[0:1] op_sel_hi:[1,0]
	v_pk_mul_f32 v[10:11], v[96:97], v[0:1] op_sel_hi:[1,0]
	v_pk_mul_f32 v[2:3], v[8:9], v[2:3]
	v_pk_mul_f32 v[4:5], v[10:11], v[4:5]
	v_cvt_pk_bf16_f32 v2, v2, v3
	v_cvt_pk_bf16_f32 v3, v4, v5
	global_store_dwordx2 v[6:7], v[2:3], off offset:48
	v_mov_b64_e32 v[2:3], v[232:233]
	v_mov_b64_e32 v[4:5], v[234:235]
	v_pk_mul_f32 v[8:9], v[66:67], v[0:1] op_sel_hi:[1,0]
	v_pk_mul_f32 v[10:11], v[68:69], v[0:1] op_sel_hi:[1,0]
	v_pk_mul_f32 v[2:3], v[8:9], v[2:3]
	v_pk_mul_f32 v[4:5], v[10:11], v[4:5]
	v_cvt_pk_bf16_f32 v2, v2, v3
	v_cvt_pk_bf16_f32 v3, v4, v5
	global_store_dwordx2 v[6:7], v[2:3], off offset:64
	v_mov_b64_e32 v[2:3], v[236:237]
	v_mov_b64_e32 v[4:5], v[238:239]
	v_pk_mul_f32 v[8:9], v[70:71], v[0:1] op_sel_hi:[1,0]
	v_pk_mul_f32 v[10:11], v[72:73], v[0:1] op_sel_hi:[1,0]
	v_pk_mul_f32 v[2:3], v[8:9], v[2:3]
	v_pk_mul_f32 v[4:5], v[10:11], v[4:5]
	v_cvt_pk_bf16_f32 v2, v2, v3
	v_cvt_pk_bf16_f32 v3, v4, v5
	global_store_dwordx2 v[6:7], v[2:3], off offset:80
	v_mov_b64_e32 v[2:3], v[240:241]
	v_mov_b64_e32 v[4:5], v[242:243]
	v_pk_mul_f32 v[8:9], v[74:75], v[0:1] op_sel_hi:[1,0]
	v_pk_mul_f32 v[10:11], v[76:77], v[0:1] op_sel_hi:[1,0]
	v_pk_mul_f32 v[2:3], v[8:9], v[2:3]
	v_pk_mul_f32 v[4:5], v[10:11], v[4:5]
	v_cvt_pk_bf16_f32 v2, v2, v3
	v_cvt_pk_bf16_f32 v3, v4, v5
	global_store_dwordx2 v[6:7], v[2:3], off offset:96
	v_mov_b64_e32 v[2:3], v[244:245]
	v_mov_b64_e32 v[4:5], v[246:247]
	v_pk_mul_f32 v[8:9], v[78:79], v[0:1] op_sel_hi:[1,0]
	v_pk_mul_f32 v[10:11], v[80:81], v[0:1] op_sel_hi:[1,0]
	v_pk_mul_f32 v[2:3], v[8:9], v[2:3]
	v_pk_mul_f32 v[4:5], v[10:11], v[4:5]
	v_cvt_pk_bf16_f32 v2, v2, v3
	v_cvt_pk_bf16_f32 v3, v4, v5
	global_store_dwordx2 v[6:7], v[2:3], off offset:112

.LBB0_1022:
	v_lshl_add_u64 v[26:27], v[24:25], 0, s[28:29]
	global_load_dwordx4 v[28:31], v[26:27], off nt
	v_mov_b32_e32 v244, 0x6000
	v_mov_b32_e32 v245, 0
	v_lshl_add_u64 v[246:247], v[26:27], 0, v[244:245]
	global_load_dwordx4 v[64:67], v[246:247], off nt
	v_lshl_add_u64 v[246:247], v[246:247], 0, v[244:245]
	global_load_dwordx4 v[68:71], v[246:247], off nt
	v_lshl_add_u64 v[246:247], v[246:247], 0, v[244:245]
	global_load_dwordx4 v[72:75], v[246:247], off nt
	v_lshl_add_u64 v[246:247], v[246:247], 0, v[244:245]
	global_load_dwordx4 v[76:79], v[246:247], off nt
	v_lshl_add_u64 v[246:247], v[246:247], 0, v[244:245]
	global_load_dwordx4 v[80:83], v[246:247], off nt
	v_lshl_add_u64 v[246:247], v[246:247], 0, v[244:245]
	global_load_dwordx4 v[84:87], v[246:247], off nt
	v_lshl_add_u64 v[246:247], v[246:247], 0, v[244:245]
	global_load_dwordx4 v[88:91], v[246:247], off nt
	v_lshl_add_u64 v[246:247], v[246:247], 0, v[244:245]
	global_load_dwordx4 v[92:95], v[246:247], off nt
	v_lshl_add_u64 v[246:247], v[246:247], 0, v[244:245]
	global_load_dwordx4 v[96:99], v[246:247], off nt
	v_lshl_add_u64 v[246:247], v[246:247], 0, v[244:245]
	global_load_dwordx4 v[100:103], v[246:247], off nt
	v_lshl_add_u64 v[246:247], v[246:247], 0, v[244:245]
	global_load_dwordx4 v[104:107], v[246:247], off nt
	v_lshl_add_u64 v[246:247], v[246:247], 0, v[244:245]
	global_load_dwordx4 v[108:111], v[246:247], off nt
	v_lshl_add_u64 v[246:247], v[246:247], 0, v[244:245]
	global_load_dwordx4 v[112:115], v[246:247], off nt
	v_lshl_add_u64 v[246:247], v[246:247], 0, v[244:245]
	global_load_dwordx4 v[116:119], v[246:247], off nt
	v_lshl_add_u64 v[246:247], v[246:247], 0, v[244:245]
	global_load_dwordx4 v[120:123], v[246:247], off nt
	v_mov_b32_e32 v23, s1
	ds_read_b128 v[32:35], v23
	ds_read_b128 v[42:45], v23 offset:16
	ds_read_b128 v[46:49], v23 offset:32
	ds_read_b128 v[14:17], v23 offset:48
	ds_read_b128 v[50:53], v23 offset:256
	ds_read_b128 v[54:57], v23 offset:512
	s_mov_b32 s22, 0x1e000
	s_add_u32 s28, s28, 0x60000
	s_addc_u32 s29, s29, 0
	s_add_i32 s1, s1, 64
	s_cmp_eq_u32 s28, 0x180000
	s_waitcnt vmcnt(15) lgkmcnt(5)
	v_pk_fma_f32 v[10:11], v[32:33], v[28:29], v[10:11] op_sel_hi:[0,1,1]
	s_waitcnt lgkmcnt(1)
	v_pk_fma_f32 v[6:7], v[28:29], v[50:51], v[6:7] op_sel_hi:[1,0,1]
	s_waitcnt lgkmcnt(0)
	v_pk_fma_f32 v[28:29], v[28:29], v[54:55], v[2:3] op_sel_hi:[1,0,1]
	v_pk_fma_f32 v[12:13], v[32:33], v[30:31], v[12:13] op_sel_hi:[0,1,1]
	v_pk_fma_f32 v[8:9], v[30:31], v[50:51], v[8:9] op_sel_hi:[1,0,1]
	v_pk_fma_f32 v[30:31], v[30:31], v[54:55], v[4:5] op_sel_hi:[1,0,1]
	s_waitcnt vmcnt(14)
	v_pk_fma_f32 v[10:11], v[32:33], v[64:65], v[10:11] op_sel:[1, 0, 0]
	v_pk_fma_f32 v[6:7], v[64:65], v[50:51], v[6:7] op_sel:[0, 1, 0]
	v_pk_fma_f32 v[28:29], v[64:65], v[54:55], v[28:29] op_sel:[0, 1, 0]
	v_pk_fma_f32 v[12:13], v[32:33], v[66:67], v[12:13] op_sel:[1, 0, 0]
	v_pk_fma_f32 v[8:9], v[66:67], v[50:51], v[8:9] op_sel:[0, 1, 0]
	v_pk_fma_f32 v[30:31], v[66:67], v[54:55], v[30:31] op_sel:[0, 1, 0]
	v_mov_b32_e32 v32, v35
	s_waitcnt vmcnt(13)
	v_pk_fma_f32 v[10:11], v[34:35], v[68:69], v[10:11] op_sel_hi:[0, 1, 1]
	v_pk_fma_f32 v[6:7], v[68:69], v[52:53], v[6:7] op_sel_hi:[1, 0, 1]
	v_pk_fma_f32 v[28:29], v[68:69], v[56:57], v[28:29] op_sel_hi:[1, 0, 1]
	v_pk_fma_f32 v[12:13], v[34:35], v[70:71], v[12:13] op_sel_hi:[0, 1, 1]
	v_pk_fma_f32 v[8:9], v[70:71], v[52:53], v[8:9] op_sel_hi:[1, 0, 1]
	v_pk_fma_f32 v[30:31], v[70:71], v[56:57], v[30:31] op_sel_hi:[1, 0, 1]
	s_waitcnt vmcnt(12)
	v_pk_fma_f32 v[34:35], v[32:33], v[72:73], v[10:11] op_sel_hi:[0, 1, 1]
	v_mov_b32_e32 v10, v53
	v_pk_fma_f32 v[36:37], v[72:73], v[10:11], v[6:7] op_sel_hi:[1, 0, 1]
	v_mov_b32_e32 v6, v57
	v_pk_fma_f32 v[28:29], v[72:73], v[6:7], v[28:29] op_sel_hi:[1, 0, 1]
	v_pk_fma_f32 v[32:33], v[32:33], v[74:75], v[12:13] op_sel_hi:[0, 1, 1]
	v_pk_fma_f32 v[50:51], v[74:75], v[10:11], v[8:9] op_sel_hi:[1, 0, 1]
	v_pk_fma_f32 v[30:31], v[74:75], v[6:7], v[30:31] op_sel_hi:[1, 0, 1]
	ds_read_b128 v[6:9], v23 offset:272
	ds_read_b128 v[10:13], v23 offset:528
	s_waitcnt vmcnt(11)
	v_pk_fma_f32 v[34:35], v[42:43], v[76:77], v[34:35] op_sel_hi:[0, 1, 1]
	s_waitcnt lgkmcnt(1)
	v_pk_fma_f32 v[36:37], v[76:77], v[6:7], v[36:37] op_sel_hi:[1, 0, 1]
	s_waitcnt lgkmcnt(0)
	v_pk_fma_f32 v[28:29], v[76:77], v[10:11], v[28:29] op_sel_hi:[1, 0, 1]
	v_pk_fma_f32 v[32:33], v[42:43], v[78:79], v[32:33] op_sel_hi:[0, 1, 1]
	v_pk_fma_f32 v[50:51], v[78:79], v[6:7], v[50:51] op_sel_hi:[1, 0, 1]
	v_pk_fma_f32 v[30:31], v[78:79], v[10:11], v[30:31] op_sel_hi:[1, 0, 1]
	s_mov_b32 s22, 0x2a000
	s_waitcnt vmcnt(10)
	v_pk_fma_f32 v[34:35], v[42:43], v[80:81], v[34:35] op_sel:[1, 0, 0]
	v_pk_fma_f32 v[36:37], v[80:81], v[6:7], v[36:37] op_sel:[0, 1, 0]
	v_pk_fma_f32 v[28:29], v[80:81], v[10:11], v[28:29] op_sel:[0, 1, 0]
	v_pk_fma_f32 v[32:33], v[42:43], v[82:83], v[32:33] op_sel:[1, 0, 0]
	v_pk_fma_f32 v[6:7], v[82:83], v[6:7], v[50:51] op_sel:[0, 1, 0]
	v_pk_fma_f32 v[10:11], v[82:83], v[10:11], v[30:31] op_sel:[0, 1, 0]
	s_waitcnt vmcnt(9)
	v_pk_fma_f32 v[30:31], v[44:45], v[84:85], v[34:35] op_sel_hi:[0, 1, 1]
	v_pk_fma_f32 v[34:35], v[84:85], v[8:9], v[36:37] op_sel_hi:[1, 0, 1]
	v_pk_fma_f32 v[28:29], v[84:85], v[12:13], v[28:29] op_sel_hi:[1, 0, 1]
	v_pk_fma_f32 v[32:33], v[44:45], v[86:87], v[32:33] op_sel_hi:[0, 1, 1]
	v_pk_fma_f32 v[6:7], v[86:87], v[8:9], v[6:7] op_sel_hi:[1, 0, 1]
	v_pk_fma_f32 v[10:11], v[86:87], v[12:13], v[10:11] op_sel_hi:[1, 0, 1]
	v_mov_b32_e32 v8, v45
	s_mov_b32 s22, 0x36000
	s_waitcnt vmcnt(8)
	v_pk_fma_f32 v[30:31], v[8:9], v[88:89], v[30:31] op_sel_hi:[0, 1, 1]
	v_pk_fma_f32 v[32:33], v[8:9], v[90:91], v[32:33] op_sel_hi:[0, 1, 1]
	v_mov_b32_e32 v8, v9
	v_pk_fma_f32 v[36:37], v[90:91], v[8:9], v[6:7] op_sel_hi:[1, 0, 1]
	v_mov_b32_e32 v6, v13
	v_pk_fma_f32 v[34:35], v[88:89], v[8:9], v[34:35] op_sel_hi:[1, 0, 1]
	v_pk_fma_f32 v[28:29], v[88:89], v[6:7], v[28:29] op_sel_hi:[1, 0, 1]
	v_pk_fma_f32 v[42:43], v[90:91], v[6:7], v[10:11] op_sel_hi:[1, 0, 1]
	ds_read_b128 v[6:9], v23 offset:288
	ds_read_b128 v[10:13], v23 offset:544
	s_waitcnt vmcnt(7)
	v_pk_fma_f32 v[30:31], v[46:47], v[92:93], v[30:31] op_sel_hi:[0, 1, 1]
	s_waitcnt lgkmcnt(1)
	v_pk_fma_f32 v[34:35], v[92:93], v[6:7], v[34:35] op_sel_hi:[1, 0, 1]
	s_waitcnt lgkmcnt(0)
	v_pk_fma_f32 v[28:29], v[92:93], v[10:11], v[28:29] op_sel_hi:[1, 0, 1]
	v_pk_fma_f32 v[32:33], v[46:47], v[94:95], v[32:33] op_sel_hi:[0, 1, 1]
	v_pk_fma_f32 v[36:37], v[94:95], v[6:7], v[36:37] op_sel_hi:[1, 0, 1]
	v_pk_fma_f32 v[42:43], v[94:95], v[10:11], v[42:43] op_sel_hi:[1, 0, 1]
	s_mov_b32 s22, 0x5a000
	s_waitcnt vmcnt(6)
	v_pk_fma_f32 v[30:31], v[46:47], v[96:97], v[30:31] op_sel:[1, 0, 0]
	v_pk_fma_f32 v[34:35], v[96:97], v[6:7], v[34:35] op_sel:[0, 1, 0]
	v_pk_fma_f32 v[28:29], v[96:97], v[10:11], v[28:29] op_sel:[0, 1, 0]
	v_pk_fma_f32 v[32:33], v[46:47], v[98:99], v[32:33] op_sel:[1, 0, 0]
	v_pk_fma_f32 v[6:7], v[98:99], v[6:7], v[36:37] op_sel:[0, 1, 0]
	v_pk_fma_f32 v[10:11], v[98:99], v[10:11], v[42:43] op_sel:[0, 1, 0]
	s_waitcnt vmcnt(5)
	v_pk_fma_f32 v[30:31], v[48:49], v[100:101], v[30:31] op_sel_hi:[0, 1, 1]
	v_pk_fma_f32 v[34:35], v[100:101], v[8:9], v[34:35] op_sel_hi:[1, 0, 1]
	v_pk_fma_f32 v[28:29], v[100:101], v[12:13], v[28:29] op_sel_hi:[1, 0, 1]
	v_pk_fma_f32 v[32:33], v[48:49], v[102:103], v[32:33] op_sel_hi:[0, 1, 1]
	v_pk_fma_f32 v[6:7], v[102:103], v[8:9], v[6:7] op_sel_hi:[1, 0, 1]
	v_pk_fma_f32 v[10:11], v[102:103], v[12:13], v[10:11] op_sel_hi:[1, 0, 1]
	v_mov_b32_e32 v8, v49
	s_waitcnt vmcnt(4)
	v_pk_fma_f32 v[36:37], v[8:9], v[104:105], v[30:31] op_sel_hi:[0, 1, 1]
	v_pk_fma_f32 v[32:33], v[8:9], v[106:107], v[32:33] op_sel_hi:[0, 1, 1]
	v_mov_b32_e32 v8, v9
	v_pk_fma_f32 v[42:43], v[106:107], v[8:9], v[6:7] op_sel_hi:[1, 0, 1]
	v_mov_b32_e32 v6, v13
	v_pk_fma_f32 v[34:35], v[104:105], v[8:9], v[34:35] op_sel_hi:[1, 0, 1]
	v_pk_fma_f32 v[12:13], v[104:105], v[6:7], v[28:29] op_sel_hi:[1, 0, 1]
	v_pk_fma_f32 v[10:11], v[106:107], v[6:7], v[10:11] op_sel_hi:[1, 0, 1]
	ds_read_b128 v[6:9], v23 offset:304
	ds_read_b128 v[28:31], v23 offset:560
	s_waitcnt vmcnt(3)
	v_pk_fma_f32 v[36:37], v[14:15], v[108:109], v[36:37] op_sel_hi:[0, 1, 1]
	s_waitcnt lgkmcnt(1)
	v_pk_fma_f32 v[34:35], v[108:109], v[6:7], v[34:35] op_sel_hi:[1, 0, 1]
	s_waitcnt lgkmcnt(0)
	v_pk_fma_f32 v[12:13], v[108:109], v[28:29], v[12:13] op_sel_hi:[1, 0, 1]
	v_pk_fma_f32 v[32:33], v[14:15], v[110:111], v[32:33] op_sel_hi:[0, 1, 1]
	v_pk_fma_f32 v[42:43], v[110:111], v[6:7], v[42:43] op_sel_hi:[1, 0, 1]
	v_pk_fma_f32 v[10:11], v[110:111], v[28:29], v[10:11] op_sel_hi:[1, 0, 1]
	s_waitcnt vmcnt(2)
	v_pk_fma_f32 v[36:37], v[14:15], v[112:113], v[36:37] op_sel:[1, 0, 0]
	v_pk_fma_f32 v[14:15], v[14:15], v[114:115], v[32:33] op_sel:[1, 0, 0]
	v_pk_fma_f32 v[32:33], v[112:113], v[6:7], v[34:35] op_sel:[0, 1, 0]
	v_pk_fma_f32 v[12:13], v[112:113], v[28:29], v[12:13] op_sel:[0, 1, 0]
	v_pk_fma_f32 v[6:7], v[114:115], v[6:7], v[42:43] op_sel:[0, 1, 0]
	v_pk_fma_f32 v[10:11], v[114:115], v[28:29], v[10:11] op_sel:[0, 1, 0]
	s_waitcnt vmcnt(1)
	v_pk_fma_f32 v[28:29], v[16:17], v[116:117], v[36:37] op_sel_hi:[0, 1, 1]
	v_pk_fma_f32 v[32:33], v[116:117], v[8:9], v[32:33] op_sel_hi:[1, 0, 1]
	v_pk_fma_f32 v[36:37], v[116:117], v[30:31], v[12:13] op_sel_hi:[1, 0, 1]
	v_pk_fma_f32 v[14:15], v[16:17], v[118:119], v[14:15] op_sel_hi:[0, 1, 1]
	v_pk_fma_f32 v[34:35], v[118:119], v[8:9], v[6:7] op_sel_hi:[1, 0, 1]
	v_pk_fma_f32 v[42:43], v[118:119], v[30:31], v[10:11] op_sel_hi:[1, 0, 1]
	v_mov_b32_e32 v6, v17
	v_mov_b32_e32 v8, v9
	s_waitcnt vmcnt(0)
	v_pk_fma_f32 v[12:13], v[6:7], v[122:123], v[14:15] op_sel_hi:[0, 1, 1]
	v_mov_b32_e32 v14, v31
	v_pk_fma_f32 v[10:11], v[6:7], v[120:121], v[28:29] op_sel_hi:[0, 1, 1]
	v_pk_fma_f32 v[6:7], v[120:121], v[8:9], v[32:33] op_sel_hi:[1, 0, 1]
	v_pk_fma_f32 v[8:9], v[122:123], v[8:9], v[34:35] op_sel_hi:[1, 0, 1]
	v_pk_fma_f32 v[2:3], v[120:121], v[14:15], v[36:37] op_sel_hi:[1, 0, 1]
	v_pk_fma_f32 v[4:5], v[122:123], v[14:15], v[42:43] op_sel_hi:[1, 0, 1]
	s_cbranch_scc0 .LBB0_1022
	s_lshl_b32 s1, s21, 2
	s_add_i32 s0, s1, s0
	v_readlane_b32 s4, v254, 0
	s_mul_i32 s1, s0, 3
	s_mul_i32 s0, s0, 0x12000
	v_readlane_b32 s8, v254, 4
	s_mul_hi_i32 s1, s1, 0x6000
	v_readlane_b32 s9, v254, 5
	s_add_u32 s0, s8, s0
	v_lshlrev_b32_e32 v14, 2, v22
	s_addc_u32 s1, s9, s1
	v_ashrrev_i32_e32 v15, 31, v14
	v_lshl_add_u64 v[14:15], v[14:15], 2, s[0:1]
	global_store_dwordx4 v[14:15], v[10:13], off
	s_mov_b32 s0, s34
	v_readlane_b32 s5, v254, 1
	v_add_co_u32_e32 v10, vcc, s45, v14
	v_readlane_b32 s6, v254, 2
	s_nop 0
	v_addc_co_u32_e32 v11, vcc, 0, v15, vcc
	global_store_dwordx4 v[10:11], v[6:9], off
	v_readlane_b32 s7, v254, 3
	v_readlane_b32 s10, v254, 6
	v_add_co_u32_e32 v6, vcc, 0xc000, v14
	v_readlane_b32 s11, v254, 7
	s_nop 0
	v_addc_co_u32_e32 v7, vcc, 0, v15, vcc
	global_store_dwordx4 v[6:7], v[2:5], off
	s_barrier
	s_lshl_b32 s0, s0, 1
	s_add_i32 s20, s0, s20
	s_cmpk_gt_i32 s20, 0x17f
	v_readlane_b32 s12, v254, 8
	v_readlane_b32 s13, v254, 9
	v_readlane_b32 s14, v254, 10
	v_readlane_b32 s15, v254, 11
	v_readlane_b32 s16, v254, 12
	v_readlane_b32 s17, v254, 13
	v_readlane_b32 s18, v254, 14
	v_readlane_b32 s19, v254, 15
	s_cbranch_scc0 .LBB0_1019
